# v9 + P3 row loop unrolled by two with the second step's tile loads hoisted into a renamed register set
# speedup vs baseline: 1.0002x; 1.0001x over previous
.LBB0_574:
	v_lshl_add_u64 v[150:151], s[64:65], 0, v[52:53]
	v_add_co_u32_e32 v152, vcc, 0x19bcd000, v150
	s_nop 0
	v_addc_co_u32_e32 v153, vcc, 0, v151, vcc
	global_load_dwordx4 v[120:123], v[152:153], off
	v_add_co_u32_e32 v152, vcc, 0x1bccd000, v150
	s_nop 0
	v_addc_co_u32_e32 v153, vcc, 0, v151, vcc
	global_load_dwordx4 v[134:137], v[152:153], off
	v_lshl_add_u64 v[150:151], s[42:43], 0, v[52:53]
	v_add_co_u32_e32 v152, vcc, 0x19bcd000, v150
	s_nop 0
	v_addc_co_u32_e32 v153, vcc, 0, v151, vcc
	global_load_dwordx4 v[112:115], v[152:153], off
	v_add_co_u32_e32 v152, vcc, 0x1bccd000, v150
	s_nop 0
	v_addc_co_u32_e32 v153, vcc, 0, v151, vcc
	global_load_dwordx4 v[116:119], v[152:153], off
	v_lshl_add_u64 v[150:151], s[38:39], 0, v[52:53]
	v_add_co_u32_e32 v152, vcc, 0x19bcd000, v150
	s_nop 0
	v_addc_co_u32_e32 v153, vcc, 0, v151, vcc
	global_load_dwordx4 v[104:107], v[152:153], off
	v_add_co_u32_e32 v152, vcc, 0x1bccd000, v150
	s_nop 0
	v_addc_co_u32_e32 v153, vcc, 0, v151, vcc
	global_load_dwordx4 v[108:111], v[152:153], off
	v_lshl_add_u64 v[150:151], s[18:19], 0, v[52:53]
	v_add_co_u32_e32 v152, vcc, 0x19bcd000, v150
	s_nop 0
	v_addc_co_u32_e32 v153, vcc, 0, v151, vcc
	global_load_dwordx4 v[96:99], v[152:153], off
	v_add_co_u32_e32 v152, vcc, 0x1bccd000, v150
	s_nop 0
	v_addc_co_u32_e32 v153, vcc, 0, v151, vcc
	global_load_dwordx4 v[100:103], v[152:153], off
	v_lshl_add_u64 v[16:17], s[64:65], 0, v[52:53]
	v_add_co_u32_e32 v18, vcc, 0x19bc5000, v16
	v_lshl_add_u64 v[20:21], s[18:19], 0, v[52:53]
	s_nop 0
	v_addc_co_u32_e32 v19, vcc, 0, v17, vcc
	v_add_co_u32_e32 v16, vcc, 0x1bcc5000, v16
	global_load_dwordx4 v[40:43], v[18:19], off
	s_nop 0
	v_addc_co_u32_e32 v17, vcc, 0, v17, vcc
	global_load_dwordx4 v[54:57], v[16:17], off
	v_lshl_add_u64 v[16:17], s[42:43], 0, v[52:53]
	v_add_co_u32_e32 v18, vcc, s45, v16
	s_add_i32 s7, s7, 32
	s_nop 0
	v_addc_co_u32_e32 v19, vcc, 0, v17, vcc
	v_add_co_u32_e32 v16, vcc, s46, v16
	global_load_dwordx4 v[32:35], v[18:19], off
	s_nop 0
	v_addc_co_u32_e32 v17, vcc, 0, v17, vcc
	global_load_dwordx4 v[36:39], v[16:17], off
	v_lshl_add_u64 v[16:17], s[38:39], 0, v[52:53]
	v_add_co_u32_e32 v18, vcc, s45, v16
	s_waitcnt vmcnt(3)
	v_lshlrev_b32_e32 v58, 16, v43
	v_and_b32_e32 v59, 0xffff0000, v43
	v_lshlrev_b32_e32 v62, 16, v42
	v_and_b32_e32 v63, 0xffff0000, v42
	s_waitcnt vmcnt(2)
	v_lshlrev_b32_e32 v42, 16, v56
	v_and_b32_e32 v43, 0xffff0000, v56
	s_waitcnt lgkmcnt(0)
	v_pk_fma_f32 v[42:43], v[12:13], v[42:43], v[62:63]
	v_lshlrev_b32_e32 v62, 16, v41
	v_and_b32_e32 v63, 0xffff0000, v41
	v_lshlrev_b32_e32 v66, 16, v40
	v_and_b32_e32 v67, 0xffff0000, v40
	v_lshlrev_b32_e32 v40, 16, v54
	v_and_b32_e32 v41, 0xffff0000, v54
	v_lshlrev_b32_e32 v64, 16, v55
	v_and_b32_e32 v65, 0xffff0000, v55
	v_pk_fma_f32 v[40:41], v[8:9], v[40:41], v[66:67]
	v_pk_fma_f32 v[62:63], v[10:11], v[64:65], v[62:63]
	v_pk_mul_f32 v[54:55], v[40:41], v[40:41]
	v_pk_mul_f32 v[64:65], v[62:63], v[62:63]
	v_add_f32_e32 v54, v54, v55
	v_add_f32_e32 v54, v64, v54
	v_lshlrev_b32_e32 v60, 16, v57
	v_and_b32_e32 v61, 0xffff0000, v57
	v_pk_mul_f32 v[56:57], v[42:43], v[42:43]
	v_add_f32_e32 v54, v65, v54
	v_pk_fma_f32 v[58:59], v[14:15], v[60:61], v[58:59]
	v_add_f32_e32 v54, v56, v54
	v_pk_mul_f32 v[60:61], v[58:59], v[58:59]
	v_add_f32_e32 v54, v57, v54
	v_add_f32_e32 v54, v60, v54
	v_add_f32_e32 v54, v61, v54
	v_addc_co_u32_e32 v19, vcc, 0, v17, vcc
	v_add_co_u32_e32 v16, vcc, s46, v16
	s_waitcnt lgkmcnt(0)
	v_addc_co_u32_e32 v17, vcc, 0, v17, vcc
	global_load_dwordx4 v[24:27], v[18:19], off
	global_load_dwordx4 v[28:31], v[16:17], off
	s_waitcnt lgkmcnt(0)
	v_add_co_u32_e32 v16, vcc, s45, v20
	s_waitcnt lgkmcnt(0)
	v_addc_co_u32_e32 v17, vcc, 0, v21, vcc
	v_add_co_u32_e32 v20, vcc, s46, v20
	s_waitcnt lgkmcnt(0)
	v_addc_co_u32_e32 v21, vcc, 0, v21, vcc
	global_load_dwordx4 v[16:19], v[16:17], off
	s_waitcnt lgkmcnt(0)
	global_load_dwordx4 v[20:23], v[20:21], off
	s_waitcnt lgkmcnt(0)
	s_nop 1
	v_add_f32_dpp v54, v54, v54 quad_perm:[1,0,3,2] row_mask:0xf bank_mask:0xf
	s_nop 1
	v_add_f32_dpp v54, v54, v54 quad_perm:[2,3,0,1] row_mask:0xf bank_mask:0xf
	s_nop 1
	v_add_f32_dpp v54, v54, v54 row_half_mirror row_mask:0xf bank_mask:0xf
	s_nop 1
	v_add_f32_dpp v54, v54, v54 row_mirror row_mask:0xf bank_mask:0xf
	s_nop 1
	v_readlane_b32 s98, v54, 0
	v_readlane_b32 s99, v54, 16
	v_readlane_b32 s100, v54, 32
	v_readlane_b32 s101, v54, 48
	s_nop 1
	v_mov_b32_e32 v54, s98
	v_add_f32_e32 v54, s99, v54
	v_add_f32_e32 v54, s100, v54
	v_add_f32_e32 v54, s101, v54
	v_fmamk_f32 v54, v54, 0x3b000000, v77
	v_rsq_f32_e32 v54, v54
	s_nop 0
	v_pk_mul_f32 v[40:41], v[40:41], v[54:55] op_sel_hi:[1,0]
	v_pk_mul_f32 v[56:57], v[62:63], v[54:55] op_sel_hi:[1,0]
	v_pk_mul_f32 v[42:43], v[42:43], v[54:55] op_sel_hi:[1,0]
	v_pk_mul_f32 v[54:55], v[58:59], v[54:55] op_sel_hi:[1,0]
	v_pk_mul_f32 v[40:41], v[0:1], v[40:41]
	v_pk_mul_f32 v[56:57], v[2:3], v[56:57]
	v_pk_mul_f32 v[42:43], v[4:5], v[42:43]
	v_pk_mul_f32 v[54:55], v[6:7], v[54:55]
	v_cvt_pk_bf16_f32 v40, v40, v41
	v_cvt_pk_bf16_f32 v41, v56, v57
	v_cvt_pk_bf16_f32 v42, v42, v43
	v_cvt_pk_bf16_f32 v43, v54, v55
	v_lshl_add_u64 v[54:55], s[60:61], 0, v[52:53]
	global_store_dwordx4 v[54:55], v[40:43], off
	s_waitcnt vmcnt(6)
	v_lshlrev_b32_e32 v54, 16, v34
	v_and_b32_e32 v55, 0xffff0000, v34
	v_lshlrev_b32_e32 v40, 16, v35
	v_and_b32_e32 v41, 0xffff0000, v35
	s_waitcnt vmcnt(5)
	v_lshlrev_b32_e32 v34, 16, v38
	v_and_b32_e32 v35, 0xffff0000, v38
	v_pk_fma_f32 v[34:35], v[12:13], v[34:35], v[54:55]
	v_lshlrev_b32_e32 v54, 16, v33
	v_and_b32_e32 v55, 0xffff0000, v33
	v_lshlrev_b32_e32 v58, 16, v32
	v_and_b32_e32 v59, 0xffff0000, v32
	v_lshlrev_b32_e32 v32, 16, v36
	v_and_b32_e32 v33, 0xffff0000, v36
	v_lshlrev_b32_e32 v56, 16, v37
	v_and_b32_e32 v57, 0xffff0000, v37
	v_pk_fma_f32 v[32:33], v[8:9], v[32:33], v[58:59]
	v_pk_fma_f32 v[54:55], v[10:11], v[56:57], v[54:55]
	v_pk_mul_f32 v[36:37], v[32:33], v[32:33]
	v_pk_mul_f32 v[56:57], v[54:55], v[54:55]
	v_add_f32_e32 v36, v36, v37
	v_add_f32_e32 v36, v56, v36
	v_lshlrev_b32_e32 v42, 16, v39
	v_and_b32_e32 v43, 0xffff0000, v39
	v_pk_mul_f32 v[38:39], v[34:35], v[34:35]
	v_add_f32_e32 v36, v57, v36
	v_pk_fma_f32 v[40:41], v[14:15], v[42:43], v[40:41]
	v_add_f32_e32 v36, v38, v36
	v_pk_mul_f32 v[42:43], v[40:41], v[40:41]
	v_add_f32_e32 v36, v39, v36
	v_add_f32_e32 v36, v42, v36
	v_add_f32_e32 v36, v43, v36
	s_waitcnt lgkmcnt(0)
	s_waitcnt lgkmcnt(0)
	s_waitcnt lgkmcnt(0)
	s_waitcnt lgkmcnt(0)
	s_waitcnt lgkmcnt(0)
	s_waitcnt lgkmcnt(0)
	s_nop 1
	v_add_f32_dpp v36, v36, v36 quad_perm:[1,0,3,2] row_mask:0xf bank_mask:0xf
	s_nop 1
	v_add_f32_dpp v36, v36, v36 quad_perm:[2,3,0,1] row_mask:0xf bank_mask:0xf
	s_nop 1
	v_add_f32_dpp v36, v36, v36 row_half_mirror row_mask:0xf bank_mask:0xf
	s_nop 1
	v_add_f32_dpp v36, v36, v36 row_mirror row_mask:0xf bank_mask:0xf
	s_nop 1
	v_readlane_b32 s98, v36, 0
	v_readlane_b32 s99, v36, 16
	v_readlane_b32 s100, v36, 32
	v_readlane_b32 s101, v36, 48
	s_nop 1
	v_mov_b32_e32 v36, s98
	v_add_f32_e32 v36, s99, v36
	v_add_f32_e32 v36, s100, v36
	v_add_f32_e32 v36, s101, v36
	v_fmamk_f32 v36, v36, 0x3b000000, v77
	v_rsq_f32_e32 v36, v36
	s_nop 0
	v_pk_mul_f32 v[32:33], v[32:33], v[36:37] op_sel_hi:[1,0]
	v_pk_mul_f32 v[38:39], v[54:55], v[36:37] op_sel_hi:[1,0]
	v_pk_mul_f32 v[34:35], v[34:35], v[36:37] op_sel_hi:[1,0]
	v_pk_mul_f32 v[36:37], v[40:41], v[36:37] op_sel_hi:[1,0]
	v_pk_mul_f32 v[32:33], v[0:1], v[32:33]
	v_pk_mul_f32 v[38:39], v[2:3], v[38:39]
	v_pk_mul_f32 v[34:35], v[4:5], v[34:35]
	v_pk_mul_f32 v[36:37], v[6:7], v[36:37]
	v_cvt_pk_bf16_f32 v32, v32, v33
	v_cvt_pk_bf16_f32 v33, v38, v39
	v_cvt_pk_bf16_f32 v34, v34, v35
	v_cvt_pk_bf16_f32 v35, v36, v37
	v_lshl_add_u64 v[36:37], s[40:41], 0, v[52:53]
	global_store_dwordx4 v[36:37], v[32:35], off
	s_waitcnt vmcnt(5)
	v_lshlrev_b32_e32 v36, 16, v26
	v_and_b32_e32 v37, 0xffff0000, v26
	v_lshlrev_b32_e32 v32, 16, v27
	v_and_b32_e32 v33, 0xffff0000, v27
	s_waitcnt vmcnt(4)
	v_lshlrev_b32_e32 v26, 16, v30
	v_and_b32_e32 v27, 0xffff0000, v30
	v_pk_fma_f32 v[26:27], v[12:13], v[26:27], v[36:37]
	v_lshlrev_b32_e32 v36, 16, v25
	v_and_b32_e32 v37, 0xffff0000, v25
	v_lshlrev_b32_e32 v40, 16, v24
	v_and_b32_e32 v41, 0xffff0000, v24
	v_lshlrev_b32_e32 v24, 16, v28
	v_and_b32_e32 v25, 0xffff0000, v28
	v_lshlrev_b32_e32 v38, 16, v29
	v_and_b32_e32 v39, 0xffff0000, v29
	v_pk_fma_f32 v[24:25], v[8:9], v[24:25], v[40:41]
	v_pk_fma_f32 v[36:37], v[10:11], v[38:39], v[36:37]
	v_pk_mul_f32 v[28:29], v[24:25], v[24:25]
	v_pk_mul_f32 v[38:39], v[36:37], v[36:37]
	v_add_f32_e32 v28, v28, v29
	v_add_f32_e32 v28, v38, v28
	v_lshlrev_b32_e32 v34, 16, v31
	v_and_b32_e32 v35, 0xffff0000, v31
	v_pk_mul_f32 v[30:31], v[26:27], v[26:27]
	v_add_f32_e32 v28, v39, v28
	v_pk_fma_f32 v[32:33], v[14:15], v[34:35], v[32:33]
	v_add_f32_e32 v28, v30, v28
	v_pk_mul_f32 v[34:35], v[32:33], v[32:33]
	v_add_f32_e32 v28, v31, v28
	v_add_f32_e32 v28, v34, v28
	v_add_f32_e32 v28, v35, v28
	s_waitcnt lgkmcnt(0)
	s_waitcnt lgkmcnt(0)
	s_waitcnt lgkmcnt(0)
	s_waitcnt lgkmcnt(0)
	s_waitcnt lgkmcnt(0)
	s_waitcnt lgkmcnt(0)
	s_nop 1
	v_add_f32_dpp v28, v28, v28 quad_perm:[1,0,3,2] row_mask:0xf bank_mask:0xf
	s_nop 1
	v_add_f32_dpp v28, v28, v28 quad_perm:[2,3,0,1] row_mask:0xf bank_mask:0xf
	s_nop 1
	v_add_f32_dpp v28, v28, v28 row_half_mirror row_mask:0xf bank_mask:0xf
	s_nop 1
	v_add_f32_dpp v28, v28, v28 row_mirror row_mask:0xf bank_mask:0xf
	s_nop 1
	v_readlane_b32 s98, v28, 0
	v_readlane_b32 s99, v28, 16
	v_readlane_b32 s100, v28, 32
	v_readlane_b32 s101, v28, 48
	s_nop 1
	v_mov_b32_e32 v28, s98
	v_add_f32_e32 v28, s99, v28
	v_add_f32_e32 v28, s100, v28
	v_add_f32_e32 v28, s101, v28
	v_fmamk_f32 v28, v28, 0x3b000000, v77
	v_rsq_f32_e32 v28, v28
	s_nop 0
	v_pk_mul_f32 v[24:25], v[24:25], v[28:29] op_sel_hi:[1,0]
	v_pk_mul_f32 v[30:31], v[36:37], v[28:29] op_sel_hi:[1,0]
	v_pk_mul_f32 v[26:27], v[26:27], v[28:29] op_sel_hi:[1,0]
	v_pk_mul_f32 v[28:29], v[32:33], v[28:29] op_sel_hi:[1,0]
	v_pk_mul_f32 v[24:25], v[0:1], v[24:25]
	v_pk_mul_f32 v[30:31], v[2:3], v[30:31]
	v_pk_mul_f32 v[26:27], v[4:5], v[26:27]
	v_pk_mul_f32 v[28:29], v[6:7], v[28:29]
	v_cvt_pk_bf16_f32 v24, v24, v25
	v_cvt_pk_bf16_f32 v25, v30, v31
	v_cvt_pk_bf16_f32 v26, v26, v27
	v_cvt_pk_bf16_f32 v27, v28, v29
	v_lshl_add_u64 v[28:29], s[36:37], 0, v[52:53]
	global_store_dwordx4 v[28:29], v[24:27], off
	s_waitcnt vmcnt(4)
	v_lshlrev_b32_e32 v28, 16, v18
	v_and_b32_e32 v29, 0xffff0000, v18
	v_lshlrev_b32_e32 v24, 16, v19
	v_and_b32_e32 v25, 0xffff0000, v19
	s_waitcnt vmcnt(3)
	v_lshlrev_b32_e32 v18, 16, v22
	v_and_b32_e32 v19, 0xffff0000, v22
	v_pk_fma_f32 v[18:19], v[12:13], v[18:19], v[28:29]
	v_lshlrev_b32_e32 v28, 16, v17
	v_and_b32_e32 v29, 0xffff0000, v17
	v_lshlrev_b32_e32 v32, 16, v16
	v_and_b32_e32 v33, 0xffff0000, v16
	v_lshlrev_b32_e32 v16, 16, v20
	v_and_b32_e32 v17, 0xffff0000, v20
	v_lshlrev_b32_e32 v30, 16, v21
	v_and_b32_e32 v31, 0xffff0000, v21
	v_pk_fma_f32 v[16:17], v[8:9], v[16:17], v[32:33]
	v_pk_fma_f32 v[28:29], v[10:11], v[30:31], v[28:29]
	v_pk_mul_f32 v[20:21], v[16:17], v[16:17]
	v_pk_mul_f32 v[30:31], v[28:29], v[28:29]
	v_add_f32_e32 v20, v20, v21
	v_add_f32_e32 v20, v30, v20
	v_lshlrev_b32_e32 v26, 16, v23
	v_and_b32_e32 v27, 0xffff0000, v23
	v_pk_mul_f32 v[22:23], v[18:19], v[18:19]
	v_add_f32_e32 v20, v31, v20
	v_pk_fma_f32 v[24:25], v[14:15], v[26:27], v[24:25]
	v_add_f32_e32 v20, v22, v20
	v_pk_mul_f32 v[26:27], v[24:25], v[24:25]
	v_add_f32_e32 v20, v23, v20
	v_add_f32_e32 v20, v26, v20
	v_add_f32_e32 v20, v27, v20
	s_waitcnt lgkmcnt(0)
	s_waitcnt lgkmcnt(0)
	s_waitcnt lgkmcnt(0)
	s_waitcnt lgkmcnt(0)
	s_waitcnt lgkmcnt(0)
	s_waitcnt lgkmcnt(0)
	s_nop 1
	v_add_f32_dpp v20, v20, v20 quad_perm:[1,0,3,2] row_mask:0xf bank_mask:0xf
	s_nop 1
	v_add_f32_dpp v20, v20, v20 quad_perm:[2,3,0,1] row_mask:0xf bank_mask:0xf
	s_nop 1
	v_add_f32_dpp v20, v20, v20 row_half_mirror row_mask:0xf bank_mask:0xf
	s_nop 1
	v_add_f32_dpp v20, v20, v20 row_mirror row_mask:0xf bank_mask:0xf
	s_nop 1
	v_readlane_b32 s98, v20, 0
	v_readlane_b32 s99, v20, 16
	v_readlane_b32 s100, v20, 32
	v_readlane_b32 s101, v20, 48
	s_nop 1
	v_mov_b32_e32 v20, s98
	v_add_f32_e32 v20, s99, v20
	v_add_f32_e32 v20, s100, v20
	v_add_f32_e32 v20, s101, v20
	v_fmamk_f32 v20, v20, 0x3b000000, v77
	v_rsq_f32_e32 v20, v20
	s_nop 0
	v_pk_mul_f32 v[16:17], v[16:17], v[20:21] op_sel_hi:[1,0]
	v_pk_mul_f32 v[22:23], v[28:29], v[20:21] op_sel_hi:[1,0]
	v_pk_mul_f32 v[18:19], v[18:19], v[20:21] op_sel_hi:[1,0]
	v_pk_mul_f32 v[20:21], v[24:25], v[20:21] op_sel_hi:[1,0]
	v_pk_mul_f32 v[18:19], v[4:5], v[18:19]
	v_pk_mul_f32 v[20:21], v[6:7], v[20:21]
	v_cvt_pk_bf16_f32 v18, v18, v19
	v_cvt_pk_bf16_f32 v19, v20, v21
	v_lshl_add_u64 v[20:21], s[16:17], 0, v[52:53]
	s_add_u32 s16, s16, 0x10000
	s_addc_u32 s17, s17, 0
	s_add_u32 s18, s18, 0x8000
	s_addc_u32 s19, s19, 0
	s_add_u32 s36, s36, 0x10000
	s_addc_u32 s37, s37, 0
	s_add_u32 s38, s38, 0x8000
	s_addc_u32 s39, s39, 0
	s_add_u32 s40, s40, 0x10000
	s_addc_u32 s41, s41, 0
	s_add_u32 s42, s42, 0x8000
	s_addc_u32 s43, s43, 0
	s_add_u32 s60, s60, 0x10000
	s_addc_u32 s61, s61, 0
	s_add_u32 s64, s64, 0x8000
	v_pk_mul_f32 v[16:17], v[0:1], v[16:17]
	v_pk_mul_f32 v[22:23], v[2:3], v[22:23]
	s_addc_u32 s65, s65, 0
	v_cvt_pk_bf16_f32 v16, v16, v17
	v_cvt_pk_bf16_f32 v17, v22, v23
	global_store_dwordx4 v[20:21], v[16:19], off
	s_nop 0
	s_nop 0
	s_add_i32 s7, s7, 32
	s_nop 0
	s_nop 0
	v_lshlrev_b32_e32 v138, 16, v123
	v_and_b32_e32 v139, 0xffff0000, v123
	v_lshlrev_b32_e32 v142, 16, v122
	v_and_b32_e32 v143, 0xffff0000, v122
	v_lshlrev_b32_e32 v122, 16, v136
	v_and_b32_e32 v123, 0xffff0000, v136
	s_waitcnt lgkmcnt(0)
	v_pk_fma_f32 v[122:123], v[12:13], v[122:123], v[142:143]
	v_lshlrev_b32_e32 v142, 16, v121
	v_and_b32_e32 v143, 0xffff0000, v121
	v_lshlrev_b32_e32 v146, 16, v120
	v_and_b32_e32 v147, 0xffff0000, v120
	v_lshlrev_b32_e32 v120, 16, v134
	v_and_b32_e32 v121, 0xffff0000, v134
	v_lshlrev_b32_e32 v144, 16, v135
	v_and_b32_e32 v145, 0xffff0000, v135
	v_pk_fma_f32 v[120:121], v[8:9], v[120:121], v[146:147]
	v_pk_fma_f32 v[142:143], v[10:11], v[144:145], v[142:143]
	v_pk_mul_f32 v[134:135], v[120:121], v[120:121]
	v_pk_mul_f32 v[144:145], v[142:143], v[142:143]
	v_add_f32_e32 v134, v134, v135
	v_add_f32_e32 v134, v144, v134
	v_lshlrev_b32_e32 v140, 16, v137
	v_and_b32_e32 v141, 0xffff0000, v137
	v_pk_mul_f32 v[136:137], v[122:123], v[122:123]
	v_add_f32_e32 v134, v145, v134
	v_pk_fma_f32 v[138:139], v[14:15], v[140:141], v[138:139]
	v_add_f32_e32 v134, v136, v134
	v_pk_mul_f32 v[140:141], v[138:139], v[138:139]
	v_add_f32_e32 v134, v137, v134
	v_add_f32_e32 v134, v140, v134
	v_add_f32_e32 v134, v141, v134
	s_waitcnt lgkmcnt(0)
	s_waitcnt lgkmcnt(0)
	s_waitcnt lgkmcnt(0)
	s_waitcnt lgkmcnt(0)
	s_waitcnt lgkmcnt(0)
	s_waitcnt lgkmcnt(0)
	s_nop 1
	v_add_f32_dpp v134, v134, v134 quad_perm:[1,0,3,2] row_mask:0xf bank_mask:0xf
	s_nop 1
	v_add_f32_dpp v134, v134, v134 quad_perm:[2,3,0,1] row_mask:0xf bank_mask:0xf
	s_nop 1
	v_add_f32_dpp v134, v134, v134 row_half_mirror row_mask:0xf bank_mask:0xf
	s_nop 1
	v_add_f32_dpp v134, v134, v134 row_mirror row_mask:0xf bank_mask:0xf
	s_nop 1
	v_readlane_b32 s98, v134, 0
	v_readlane_b32 s99, v134, 16
	v_readlane_b32 s100, v134, 32
	v_readlane_b32 s101, v134, 48
	s_nop 1
	v_mov_b32_e32 v134, s98
	v_add_f32_e32 v134, s99, v134
	v_add_f32_e32 v134, s100, v134
	v_add_f32_e32 v134, s101, v134
	v_fmamk_f32 v134, v134, 0x3b000000, v77
	v_rsq_f32_e32 v134, v134
	s_nop 0
	v_pk_mul_f32 v[120:121], v[120:121], v[134:135] op_sel_hi:[1,0]
	v_pk_mul_f32 v[136:137], v[142:143], v[134:135] op_sel_hi:[1,0]
	v_pk_mul_f32 v[122:123], v[122:123], v[134:135] op_sel_hi:[1,0]
	v_pk_mul_f32 v[134:135], v[138:139], v[134:135] op_sel_hi:[1,0]
	v_pk_mul_f32 v[120:121], v[0:1], v[120:121]
	v_pk_mul_f32 v[136:137], v[2:3], v[136:137]
	v_pk_mul_f32 v[122:123], v[4:5], v[122:123]
	v_pk_mul_f32 v[134:135], v[6:7], v[134:135]
	v_cvt_pk_bf16_f32 v120, v120, v121
	v_cvt_pk_bf16_f32 v121, v136, v137
	v_cvt_pk_bf16_f32 v122, v122, v123
	v_cvt_pk_bf16_f32 v123, v134, v135
	v_lshl_add_u64 v[134:135], s[60:61], 0, v[52:53]
	global_store_dwordx4 v[134:135], v[120:123], off
	v_lshlrev_b32_e32 v134, 16, v114
	v_and_b32_e32 v135, 0xffff0000, v114
	v_lshlrev_b32_e32 v120, 16, v115
	v_and_b32_e32 v121, 0xffff0000, v115
	v_lshlrev_b32_e32 v114, 16, v118
	v_and_b32_e32 v115, 0xffff0000, v118
	v_pk_fma_f32 v[114:115], v[12:13], v[114:115], v[134:135]
	v_lshlrev_b32_e32 v134, 16, v113
	v_and_b32_e32 v135, 0xffff0000, v113
	v_lshlrev_b32_e32 v138, 16, v112
	v_and_b32_e32 v139, 0xffff0000, v112
	v_lshlrev_b32_e32 v112, 16, v116
	v_and_b32_e32 v113, 0xffff0000, v116
	v_lshlrev_b32_e32 v136, 16, v117
	v_and_b32_e32 v137, 0xffff0000, v117
	v_pk_fma_f32 v[112:113], v[8:9], v[112:113], v[138:139]
	v_pk_fma_f32 v[134:135], v[10:11], v[136:137], v[134:135]
	v_pk_mul_f32 v[116:117], v[112:113], v[112:113]
	v_pk_mul_f32 v[136:137], v[134:135], v[134:135]
	v_add_f32_e32 v116, v116, v117
	v_add_f32_e32 v116, v136, v116
	v_lshlrev_b32_e32 v122, 16, v119
	v_and_b32_e32 v123, 0xffff0000, v119
	v_pk_mul_f32 v[118:119], v[114:115], v[114:115]
	v_add_f32_e32 v116, v137, v116
	v_pk_fma_f32 v[120:121], v[14:15], v[122:123], v[120:121]
	v_add_f32_e32 v116, v118, v116
	v_pk_mul_f32 v[122:123], v[120:121], v[120:121]
	v_add_f32_e32 v116, v119, v116
	v_add_f32_e32 v116, v122, v116
	v_add_f32_e32 v116, v123, v116
	s_waitcnt lgkmcnt(0)
	s_waitcnt lgkmcnt(0)
	s_waitcnt lgkmcnt(0)
	s_waitcnt lgkmcnt(0)
	s_waitcnt lgkmcnt(0)
	s_waitcnt lgkmcnt(0)
	s_nop 1
	v_add_f32_dpp v116, v116, v116 quad_perm:[1,0,3,2] row_mask:0xf bank_mask:0xf
	s_nop 1
	v_add_f32_dpp v116, v116, v116 quad_perm:[2,3,0,1] row_mask:0xf bank_mask:0xf
	s_nop 1
	v_add_f32_dpp v116, v116, v116 row_half_mirror row_mask:0xf bank_mask:0xf
	s_nop 1
	v_add_f32_dpp v116, v116, v116 row_mirror row_mask:0xf bank_mask:0xf
	s_nop 1
	v_readlane_b32 s98, v116, 0
	v_readlane_b32 s99, v116, 16
	v_readlane_b32 s100, v116, 32
	v_readlane_b32 s101, v116, 48
	s_nop 1
	v_mov_b32_e32 v116, s98
	v_add_f32_e32 v116, s99, v116
	v_add_f32_e32 v116, s100, v116
	v_add_f32_e32 v116, s101, v116
	v_fmamk_f32 v116, v116, 0x3b000000, v77
	v_rsq_f32_e32 v116, v116
	s_nop 0
	v_pk_mul_f32 v[112:113], v[112:113], v[116:117] op_sel_hi:[1,0]
	v_pk_mul_f32 v[118:119], v[134:135], v[116:117] op_sel_hi:[1,0]
	v_pk_mul_f32 v[114:115], v[114:115], v[116:117] op_sel_hi:[1,0]
	v_pk_mul_f32 v[116:117], v[120:121], v[116:117] op_sel_hi:[1,0]
	v_pk_mul_f32 v[112:113], v[0:1], v[112:113]
	v_pk_mul_f32 v[118:119], v[2:3], v[118:119]
	v_pk_mul_f32 v[114:115], v[4:5], v[114:115]
	v_pk_mul_f32 v[116:117], v[6:7], v[116:117]
	v_cvt_pk_bf16_f32 v112, v112, v113
	v_cvt_pk_bf16_f32 v113, v118, v119
	v_cvt_pk_bf16_f32 v114, v114, v115
	v_cvt_pk_bf16_f32 v115, v116, v117
	v_lshl_add_u64 v[116:117], s[40:41], 0, v[52:53]
	global_store_dwordx4 v[116:117], v[112:115], off
	v_lshlrev_b32_e32 v116, 16, v106
	v_and_b32_e32 v117, 0xffff0000, v106
	v_lshlrev_b32_e32 v112, 16, v107
	v_and_b32_e32 v113, 0xffff0000, v107
	v_lshlrev_b32_e32 v106, 16, v110
	v_and_b32_e32 v107, 0xffff0000, v110
	v_pk_fma_f32 v[106:107], v[12:13], v[106:107], v[116:117]
	v_lshlrev_b32_e32 v116, 16, v105
	v_and_b32_e32 v117, 0xffff0000, v105
	v_lshlrev_b32_e32 v120, 16, v104
	v_and_b32_e32 v121, 0xffff0000, v104
	v_lshlrev_b32_e32 v104, 16, v108
	v_and_b32_e32 v105, 0xffff0000, v108
	v_lshlrev_b32_e32 v118, 16, v109
	v_and_b32_e32 v119, 0xffff0000, v109
	v_pk_fma_f32 v[104:105], v[8:9], v[104:105], v[120:121]
	v_pk_fma_f32 v[116:117], v[10:11], v[118:119], v[116:117]
	v_pk_mul_f32 v[108:109], v[104:105], v[104:105]
	v_pk_mul_f32 v[118:119], v[116:117], v[116:117]
	v_add_f32_e32 v108, v108, v109
	v_add_f32_e32 v108, v118, v108
	v_lshlrev_b32_e32 v114, 16, v111
	v_and_b32_e32 v115, 0xffff0000, v111
	v_pk_mul_f32 v[110:111], v[106:107], v[106:107]
	v_add_f32_e32 v108, v119, v108
	v_pk_fma_f32 v[112:113], v[14:15], v[114:115], v[112:113]
	v_add_f32_e32 v108, v110, v108
	v_pk_mul_f32 v[114:115], v[112:113], v[112:113]
	v_add_f32_e32 v108, v111, v108
	v_add_f32_e32 v108, v114, v108
	v_add_f32_e32 v108, v115, v108
	s_waitcnt lgkmcnt(0)
	s_waitcnt lgkmcnt(0)
	s_waitcnt lgkmcnt(0)
	s_waitcnt lgkmcnt(0)
	s_waitcnt lgkmcnt(0)
	s_waitcnt lgkmcnt(0)
	s_nop 1
	v_add_f32_dpp v108, v108, v108 quad_perm:[1,0,3,2] row_mask:0xf bank_mask:0xf
	s_nop 1
	v_add_f32_dpp v108, v108, v108 quad_perm:[2,3,0,1] row_mask:0xf bank_mask:0xf
	s_nop 1
	v_add_f32_dpp v108, v108, v108 row_half_mirror row_mask:0xf bank_mask:0xf
	s_nop 1
	v_add_f32_dpp v108, v108, v108 row_mirror row_mask:0xf bank_mask:0xf
	s_nop 1
	v_readlane_b32 s98, v108, 0
	v_readlane_b32 s99, v108, 16
	v_readlane_b32 s100, v108, 32
	v_readlane_b32 s101, v108, 48
	s_nop 1
	v_mov_b32_e32 v108, s98
	v_add_f32_e32 v108, s99, v108
	v_add_f32_e32 v108, s100, v108
	v_add_f32_e32 v108, s101, v108
	v_fmamk_f32 v108, v108, 0x3b000000, v77
	v_rsq_f32_e32 v108, v108
	s_nop 0
	v_pk_mul_f32 v[104:105], v[104:105], v[108:109] op_sel_hi:[1,0]
	v_pk_mul_f32 v[110:111], v[116:117], v[108:109] op_sel_hi:[1,0]
	v_pk_mul_f32 v[106:107], v[106:107], v[108:109] op_sel_hi:[1,0]
	v_pk_mul_f32 v[108:109], v[112:113], v[108:109] op_sel_hi:[1,0]
	v_pk_mul_f32 v[104:105], v[0:1], v[104:105]
	v_pk_mul_f32 v[110:111], v[2:3], v[110:111]
	v_pk_mul_f32 v[106:107], v[4:5], v[106:107]
	v_pk_mul_f32 v[108:109], v[6:7], v[108:109]
	v_cvt_pk_bf16_f32 v104, v104, v105
	v_cvt_pk_bf16_f32 v105, v110, v111
	v_cvt_pk_bf16_f32 v106, v106, v107
	v_cvt_pk_bf16_f32 v107, v108, v109
	v_lshl_add_u64 v[108:109], s[36:37], 0, v[52:53]
	global_store_dwordx4 v[108:109], v[104:107], off
	v_lshlrev_b32_e32 v108, 16, v98
	v_and_b32_e32 v109, 0xffff0000, v98
	v_lshlrev_b32_e32 v104, 16, v99
	v_and_b32_e32 v105, 0xffff0000, v99
	v_lshlrev_b32_e32 v98, 16, v102
	v_and_b32_e32 v99, 0xffff0000, v102
	v_pk_fma_f32 v[98:99], v[12:13], v[98:99], v[108:109]
	v_lshlrev_b32_e32 v108, 16, v97
	v_and_b32_e32 v109, 0xffff0000, v97
	v_lshlrev_b32_e32 v112, 16, v96
	v_and_b32_e32 v113, 0xffff0000, v96
	v_lshlrev_b32_e32 v96, 16, v100
	v_and_b32_e32 v97, 0xffff0000, v100
	v_lshlrev_b32_e32 v110, 16, v101
	v_and_b32_e32 v111, 0xffff0000, v101
	v_pk_fma_f32 v[96:97], v[8:9], v[96:97], v[112:113]
	v_pk_fma_f32 v[108:109], v[10:11], v[110:111], v[108:109]
	v_pk_mul_f32 v[100:101], v[96:97], v[96:97]
	v_pk_mul_f32 v[110:111], v[108:109], v[108:109]
	v_add_f32_e32 v100, v100, v101
	v_add_f32_e32 v100, v110, v100
	v_lshlrev_b32_e32 v106, 16, v103
	v_and_b32_e32 v107, 0xffff0000, v103
	v_pk_mul_f32 v[102:103], v[98:99], v[98:99]
	v_add_f32_e32 v100, v111, v100
	v_pk_fma_f32 v[104:105], v[14:15], v[106:107], v[104:105]
	v_add_f32_e32 v100, v102, v100
	v_pk_mul_f32 v[106:107], v[104:105], v[104:105]
	v_add_f32_e32 v100, v103, v100
	v_add_f32_e32 v100, v106, v100
	v_add_f32_e32 v100, v107, v100
	s_waitcnt lgkmcnt(0)
	s_waitcnt lgkmcnt(0)
	s_waitcnt lgkmcnt(0)
	s_waitcnt lgkmcnt(0)
	s_waitcnt lgkmcnt(0)
	s_waitcnt lgkmcnt(0)
	s_nop 1
	v_add_f32_dpp v100, v100, v100 quad_perm:[1,0,3,2] row_mask:0xf bank_mask:0xf
	s_nop 1
	v_add_f32_dpp v100, v100, v100 quad_perm:[2,3,0,1] row_mask:0xf bank_mask:0xf
	s_nop 1
	v_add_f32_dpp v100, v100, v100 row_half_mirror row_mask:0xf bank_mask:0xf
	s_nop 1
	v_add_f32_dpp v100, v100, v100 row_mirror row_mask:0xf bank_mask:0xf
	s_nop 1
	v_readlane_b32 s98, v100, 0
	v_readlane_b32 s99, v100, 16
	v_readlane_b32 s100, v100, 32
	v_readlane_b32 s101, v100, 48
	s_nop 1
	v_mov_b32_e32 v100, s98
	v_add_f32_e32 v100, s99, v100
	v_add_f32_e32 v100, s100, v100
	v_add_f32_e32 v100, s101, v100
	v_fmamk_f32 v100, v100, 0x3b000000, v77
	v_rsq_f32_e32 v100, v100
	s_nop 0
	v_pk_mul_f32 v[96:97], v[96:97], v[100:101] op_sel_hi:[1,0]
	v_pk_mul_f32 v[102:103], v[108:109], v[100:101] op_sel_hi:[1,0]
	v_pk_mul_f32 v[98:99], v[98:99], v[100:101] op_sel_hi:[1,0]
	v_pk_mul_f32 v[100:101], v[104:105], v[100:101] op_sel_hi:[1,0]
	v_pk_mul_f32 v[98:99], v[4:5], v[98:99]
	v_pk_mul_f32 v[100:101], v[6:7], v[100:101]
	v_cvt_pk_bf16_f32 v98, v98, v99
	v_cvt_pk_bf16_f32 v99, v100, v101
	v_lshl_add_u64 v[100:101], s[16:17], 0, v[52:53]
	s_add_u32 s16, s16, 0x10000
	s_addc_u32 s17, s17, 0
	s_add_u32 s18, s18, 0x8000
	s_addc_u32 s19, s19, 0
	s_add_u32 s36, s36, 0x10000
	s_addc_u32 s37, s37, 0
	s_add_u32 s38, s38, 0x8000
	s_addc_u32 s39, s39, 0
	s_add_u32 s40, s40, 0x10000
	s_addc_u32 s41, s41, 0
	s_add_u32 s42, s42, 0x8000
	s_addc_u32 s43, s43, 0
	s_add_u32 s60, s60, 0x10000
	s_addc_u32 s61, s61, 0
	s_add_u32 s64, s64, 0x8000
	v_pk_mul_f32 v[96:97], v[0:1], v[96:97]
	v_pk_mul_f32 v[102:103], v[2:3], v[102:103]
	s_addc_u32 s65, s65, 0
	v_cvt_pk_bf16_f32 v96, v96, v97
	v_cvt_pk_bf16_f32 v97, v102, v103
	s_cmpk_lt_u32 s7, 0x60
	global_store_dwordx4 v[100:101], v[96:99], off
	s_cbranch_scc1 .LBB0_574
	s_branch .LBB0_561
